# scan gate stage software-pipelined: next block's LDS operands and MFMAs issued one block ahead (second register set)
# speedup vs baseline: 1.0291x; 1.0018x over previous
; #define LAS __attribute__((address_space(3)))
; __device__ __forceinline__ unsigned cvt_pk(float lo, float hi) { unsigned r; asm("v_cvt_pk_bf16_f32 %0, %1, %2" : "=v"(r) : "v"(lo), "v"(hi)); return r; }
; __device__ __forceinline__ float bflo(unsigned w) { return __uint_as_float(w << 16); }
; __device__ __forceinline__ float bfhi(unsigned w) { return __uint_as_float(w & 0xffff0000u); }
; #define MFMA16(a, b, c) __builtin_amdgcn_mfma_f32_16x16x32_bf16((a), (b), (c), 0, 0, 0)
; template <int DIR>
; __device__ __forceinline__ void rnn_scan_unit(const Params& p, LAS unsigned char* lds, int b, int g) {
;     ...
;         { const int tl0 = lane >> 3, c8 = lane & 7;
; #pragma unroll
;           for (int hh = 0; hh < 2; ++hh) { const int tl = tl0 + 8 * hh;
;               f32x4 o0 = cbv[0], o1 = cbv[1];
; #pragma unroll
;               for (int j = 0; j < 4; ++j) { const u32x4 xw_ = *(const LAS u32x4*)(xrb + (tl + j) * 64 + 8 * c8);
;                   o0[0] += cwv[j][0][0] * bflo(xw_.x); o0[1] += cwv[j][0][1] * bfhi(xw_.x); o0[2] += cwv[j][0][2] * bflo(xw_.y); o0[3] += cwv[j][0][3] * bfhi(xw_.y);
;                   o1[0] += cwv[j][1][0] * bflo(xw_.z); o1[1] += cwv[j][1][1] * bfhi(xw_.z); o1[2] += cwv[j][1][2] * bflo(xw_.w); o1[3] += cwv[j][1][3] * bfhi(xw_.w); }
;               *(LAS f32x4*)(xcf + tl * XS + 8 * c8) = o0; *(LAS f32x4*)(xcf + tl * XS + 8 * c8 + 4) = o1; } }
;         asm volatile("s_waitcnt lgkmcnt(0)" ::: "memory");
;         { const int tt = fr; const bool valid = (t0 + tt) < TT;
;           bf16x8 af[2];
; #pragma unroll
;           for (int ks = 0; ks < 2; ++ks) { const f32x4 x0 = *(const LAS f32x4*)(xcf + tt * XS + 32 * ks + 8 * fq), x1 = *(const LAS f32x4*)(xcf + tt * XS + 32 * ks + 8 * fq + 4);
;               u32x4 w; w.x = cvt_pk(x0[0], x0[1]); w.y = cvt_pk(x0[2], x0[3]); w.z = cvt_pk(x1[0], x1[1]); w.w = cvt_pk(x1[2], x1[3]); af[ks] = __builtin_bit_cast(bf16x8, w); }
; #pragma unroll
;           for (int n = 0; n < 4; ++n) { const int c4 = 16 * n + 4 * fq;
;               f32x4 ra = *(const LAS f32x4*)(cst + c4), ia = *(const LAS f32x4*)(cst + 64 + c4);
; #pragma unroll
;               for (int ks = 0; ks < 2; ++ks) { ra = MFMA16(wreg[(0 * 4 + n) * 2 + ks], af[ks], ra); ia = MFMA16(wl[((1 * 4 + n) * 2 + ks) * 64 + lane], af[ks], ia); }
.LBB0_550:
	v_add_u32_e32 v0, v123, v125
	ds_read_b128 v[88:91], v0
	ds_read_b128 v[92:95], v0 offset:128
	ds_read_b128 v[96:99], v0 offset:256
	ds_read_b128 v[100:103], v0 offset:384
	v_mov_b32_e32 v113, 0
	s_waitcnt lgkmcnt(3)
	v_lshlrev_b32_e32 v104, 16, v88
	v_and_b32_e32 v105, 0xffff0000, v88
	v_lshlrev_b32_e32 v88, 16, v89
	v_and_b32_e32 v89, 0xffff0000, v89
	v_pk_fma_f32 v[104:105], v[36:37], v[104:105], v[40:41]
	s_waitcnt lgkmcnt(2)
	v_lshlrev_b32_e32 v106, 16, v92
	v_and_b32_e32 v107, 0xffff0000, v92
	v_pk_fma_f32 v[88:89], v[38:39], v[88:89], v[42:43]
	v_lshlrev_b32_e32 v92, 16, v93
	v_and_b32_e32 v93, 0xffff0000, v93
	v_pk_fma_f32 v[104:105], v[8:9], v[106:107], v[104:105]
	s_waitcnt lgkmcnt(1)
	v_lshlrev_b32_e32 v106, 16, v96
	v_and_b32_e32 v107, 0xffff0000, v96
	v_pk_fma_f32 v[88:89], v[10:11], v[92:93], v[88:89]
	v_lshlrev_b32_e32 v92, 16, v97
	v_and_b32_e32 v93, 0xffff0000, v97
	v_pk_fma_f32 v[104:105], v[12:13], v[106:107], v[104:105]
	s_waitcnt lgkmcnt(0)
	v_lshlrev_b32_e32 v106, 16, v100
	v_and_b32_e32 v107, 0xffff0000, v100
	v_pk_fma_f32 v[88:89], v[14:15], v[92:93], v[88:89]
	v_lshlrev_b32_e32 v92, 16, v101
	v_and_b32_e32 v93, 0xffff0000, v101
	v_pk_fma_f32 v[104:105], v[20:21], v[106:107], v[104:105]
	v_pk_fma_f32 v[106:107], v[22:23], v[92:93], v[88:89]
	v_lshlrev_b32_e32 v88, 16, v90
	v_and_b32_e32 v89, 0xffff0000, v90
	v_pk_fma_f32 v[88:89], v[28:29], v[88:89], v[32:33]
	v_lshlrev_b32_e32 v92, 16, v94
	v_and_b32_e32 v93, 0xffff0000, v94
	v_pk_fma_f32 v[88:89], v[4:5], v[92:93], v[88:89]
	v_lshlrev_b32_e32 v92, 16, v98
	v_and_b32_e32 v93, 0xffff0000, v98
	v_pk_fma_f32 v[88:89], v[16:17], v[92:93], v[88:89]
	v_lshlrev_b32_e32 v92, 16, v102
	v_and_b32_e32 v93, 0xffff0000, v102
	v_lshlrev_b32_e32 v90, 16, v91
	v_and_b32_e32 v91, 0xffff0000, v91
	v_pk_fma_f32 v[88:89], v[24:25], v[92:93], v[88:89]
	v_pk_fma_f32 v[90:91], v[30:31], v[90:91], v[34:35]
	v_lshlrev_b32_e32 v92, 16, v95
	v_and_b32_e32 v93, 0xffff0000, v95
	v_pk_fma_f32 v[90:91], v[6:7], v[92:93], v[90:91]
	v_lshlrev_b32_e32 v92, 16, v99
	v_and_b32_e32 v93, 0xffff0000, v99
	v_pk_fma_f32 v[90:91], v[18:19], v[92:93], v[90:91]
	v_lshlrev_b32_e32 v92, 16, v103
	v_and_b32_e32 v93, 0xffff0000, v103
	v_pk_fma_f32 v[90:91], v[26:27], v[92:93], v[90:91]
	ds_write_b128 v166, v[104:107] offset:2432
	ds_write_b128 v166, v[88:91] offset:2448
	ds_read_b128 v[88:91], v167
	ds_read_b128 v[92:95], v0 offset:1152
	ds_read_b128 v[96:99], v0 offset:1280
	ds_read_b128 v[100:103], v0 offset:1408
	v_add_u32_e32 v0, s19, v160
	s_waitcnt lgkmcnt(3)
	v_lshlrev_b32_e32 v104, 16, v88
	v_and_b32_e32 v105, 0xffff0000, v88
	v_lshlrev_b32_e32 v88, 16, v89
	v_and_b32_e32 v89, 0xffff0000, v89
	v_pk_fma_f32 v[104:105], v[36:37], v[104:105], v[40:41]
	s_waitcnt lgkmcnt(2)
	v_lshlrev_b32_e32 v106, 16, v92
	v_and_b32_e32 v107, 0xffff0000, v92
	v_pk_fma_f32 v[88:89], v[38:39], v[88:89], v[42:43]
	v_lshlrev_b32_e32 v92, 16, v93
	v_and_b32_e32 v93, 0xffff0000, v93
	v_pk_fma_f32 v[104:105], v[8:9], v[106:107], v[104:105]
	s_waitcnt lgkmcnt(1)
	v_lshlrev_b32_e32 v106, 16, v96
	v_and_b32_e32 v107, 0xffff0000, v96
	v_pk_fma_f32 v[88:89], v[10:11], v[92:93], v[88:89]
	v_lshlrev_b32_e32 v92, 16, v97
	v_and_b32_e32 v93, 0xffff0000, v97
	v_pk_fma_f32 v[104:105], v[12:13], v[106:107], v[104:105]
	s_waitcnt lgkmcnt(0)
	v_lshlrev_b32_e32 v106, 16, v100
	v_and_b32_e32 v107, 0xffff0000, v100
	v_pk_fma_f32 v[88:89], v[14:15], v[92:93], v[88:89]
	v_lshlrev_b32_e32 v92, 16, v101
	v_and_b32_e32 v93, 0xffff0000, v101
	v_pk_fma_f32 v[104:105], v[20:21], v[106:107], v[104:105]
	v_pk_fma_f32 v[106:107], v[22:23], v[92:93], v[88:89]
	v_lshlrev_b32_e32 v88, 16, v90
	v_and_b32_e32 v89, 0xffff0000, v90
	v_pk_fma_f32 v[88:89], v[28:29], v[88:89], v[32:33]
	v_lshlrev_b32_e32 v92, 16, v94
	v_and_b32_e32 v93, 0xffff0000, v94
	v_pk_fma_f32 v[88:89], v[4:5], v[92:93], v[88:89]
	v_lshlrev_b32_e32 v92, 16, v98
	v_and_b32_e32 v93, 0xffff0000, v98
	v_pk_fma_f32 v[88:89], v[16:17], v[92:93], v[88:89]
	v_lshlrev_b32_e32 v92, 16, v102
	v_and_b32_e32 v93, 0xffff0000, v102
	v_lshlrev_b32_e32 v90, 16, v91
	v_and_b32_e32 v91, 0xffff0000, v91
	v_pk_fma_f32 v[88:89], v[24:25], v[92:93], v[88:89]
	v_pk_fma_f32 v[90:91], v[30:31], v[90:91], v[34:35]
	v_lshlrev_b32_e32 v92, 16, v95
	v_and_b32_e32 v93, 0xffff0000, v95
	v_pk_fma_f32 v[90:91], v[6:7], v[92:93], v[90:91]
	v_lshlrev_b32_e32 v92, 16, v99
	v_and_b32_e32 v93, 0xffff0000, v99
	v_pk_fma_f32 v[90:91], v[18:19], v[92:93], v[90:91]
	v_lshlrev_b32_e32 v92, 16, v103
	v_and_b32_e32 v93, 0xffff0000, v103
	v_pk_fma_f32 v[90:91], v[26:27], v[92:93], v[90:91]
	ds_write_b128 v166, v[104:107] offset:4608
	ds_write_b128 v166, v[88:91] offset:4624
	s_waitcnt lgkmcnt(0)
	ds_read_b128 v[88:91], v168 offset:2432
	ds_read_b128 v[92:95], v168 offset:2448
	s_waitcnt lgkmcnt(1)
	v_cvt_pk_bf16_f32 v88, v88, v89
	v_cvt_pk_bf16_f32 v89, v90, v91
	s_waitcnt lgkmcnt(0)
	v_cvt_pk_bf16_f32 v90, v92, v93
	v_cvt_pk_bf16_f32 v91, v94, v95
	ds_read_b128 v[92:95], v168 offset:2560
	ds_read_b128 v[96:99], v168 offset:2576
	s_waitcnt lgkmcnt(1)
	v_cvt_pk_bf16_f32 v92, v92, v93
	v_cvt_pk_bf16_f32 v93, v94, v95
	s_waitcnt lgkmcnt(0)
	v_cvt_pk_bf16_f32 v94, v96, v97
	v_cvt_pk_bf16_f32 v95, v98, v99
	ds_read_b128 v[96:99], v126
	ds_read_b128 v[100:103], v127
	ds_read_b128 v[104:107], v117 offset:8192
	ds_read_b128 v[228:231], v117 offset:9216
	v_cmp_gt_i32_e64 s[16:17], s86, v0
	ds_read_b128 v[232:235], v131
	ds_read_b128 v[236:239], v132
	ds_read_b128 v[240:243], v117 offset:10240
	ds_read_b128 v[108:111], v117 offset:11264
	s_waitcnt lgkmcnt(4)
; #define LAS __attribute__((address_space(3)))
; #define MFMA16(a, b, c) __builtin_amdgcn_mfma_f32_16x16x32_bf16((a), (b), (c), 0, 0, 0)
; template <int DIR>
; __device__ __forceinline__ void rnn_scan_unit(const Params& p, LAS unsigned char* lds, int b, int g) {
;     ...
;           for (int n = 0; n < 4; ++n) { const int c4 = 16 * n + 4 * fq;
;               f32x4 ra = *(const LAS f32x4*)(cst + c4), ia = *(const LAS f32x4*)(cst + 64 + c4);
; #pragma unroll
;               for (int ks = 0; ks < 2; ++ks) { ra = MFMA16(wreg[(0 * 4 + n) * 2 + ks], af[ks], ra); ia = MFMA16(wl[((1 * 4 + n) * 2 + ks) * 64 + lane], af[ks], ia); }
;               const f32x4 xv = *(const LAS f32x4*)(xcf + tt * XS + c4);
;               const f32x4 spv = *(const LAS f32x4*)(cst + 128 + c4);
;               f32x4 av, bv;
; #pragma unroll
;               for (int i = 0; i < 4; ++i) { const float r = __builtin_amdgcn_rcpf(1.0f + __builtin_amdgcn_exp2f(ra[i])), ig = __builtin_amdgcn_rcpf(1.0f + __builtin_amdgcn_exp2f(ia[i]));
;                   const float a = __builtin_amdgcn_exp2f(r * spv[i]); const float em = fmaf(-a, a, 1.0f);
;                   av[i] = valid ? a : 1.0f; bv[i] = valid ? __builtin_amdgcn_sqrtf(fmaxf(em, 0.0f)) * ig * xv[i] : 0.0f; }
;               *(LAS f32x4*)(al + tt * 64 + c4) = av; *(LAS f32x4*)(bl + tt * 64 + c4) = bv; } }
	v_mfma_f32_16x16x32_bf16 v[96:99], v[44:47], v[88:91], v[96:99]
	v_mfma_f32_16x16x32_bf16 v[100:103], v[104:107], v[88:91], v[100:103]
	v_mfma_f32_16x16x32_bf16 v[96:99], v[48:51], v[92:95], v[96:99]
	v_mfma_f32_16x16x32_bf16 v[100:103], v[228:231], v[92:95], v[100:103]
	ds_read_b128 v[104:107], v129
	ds_read_b128 v[228:231], v128 offset:2432
	s_nop 7
	v_exp_f32_e32 v96, v96
	v_exp_f32_e32 v97, v97
	v_exp_f32_e32 v98, v98
	v_exp_f32_e32 v99, v99
	v_exp_f32_e32 v100, v100
	v_exp_f32_e32 v101, v101
	v_exp_f32_e32 v102, v102
	v_exp_f32_e32 v103, v103
	v_add_f32_e32 v96, 1.0, v96
	v_add_f32_e32 v97, 1.0, v97
	v_add_f32_e32 v98, 1.0, v98
	v_add_f32_e32 v99, 1.0, v99
	v_add_f32_e32 v100, 1.0, v100
	v_add_f32_e32 v101, 1.0, v101
	v_add_f32_e32 v102, 1.0, v102
	v_add_f32_e32 v103, 1.0, v103
	v_rcp_f32_e32 v96, v96
	v_rcp_f32_e32 v97, v97
	v_rcp_f32_e32 v98, v98
	v_rcp_f32_e32 v99, v99
	v_rcp_f32_e32 v100, v100
	v_rcp_f32_e32 v101, v101
	v_rcp_f32_e32 v102, v102
	v_rcp_f32_e32 v103, v103
	s_waitcnt lgkmcnt(0)
	v_mfma_f32_16x16x32_bf16 v[232:235], v[52:55], v[88:91], v[232:235]
	v_mfma_f32_16x16x32_bf16 v[236:239], v[240:243], v[88:91], v[236:239]
	v_mfma_f32_16x16x32_bf16 v[232:235], v[56:59], v[92:95], v[232:235]
	v_mfma_f32_16x16x32_bf16 v[236:239], v[108:111], v[92:95], v[236:239]
	ds_read_b128 v[240:243], v133
	ds_read_b128 v[108:111], v128 offset:2496
	v_mul_f32_e32 v96, v96, v104
	v_mul_f32_e32 v97, v97, v105
	v_mul_f32_e32 v98, v98, v106
	v_mul_f32_e32 v99, v99, v107
	v_exp_f32_e32 v96, v96
	v_exp_f32_e32 v97, v97
	v_exp_f32_e32 v98, v98
	v_exp_f32_e32 v99, v99
	v_fma_f32 v112, -v96, v96, 1.0
	v_fma_f32 v113, -v97, v97, 1.0
	v_fma_f32 v114, -v98, v98, 1.0
	v_fma_f32 v115, -v99, v99, 1.0
	v_max_f32_e32 v112, 0, v112
	v_max_f32_e32 v113, 0, v113
	v_max_f32_e32 v114, 0, v114
	v_max_f32_e32 v115, 0, v115
	v_sqrt_f32_e32 v112, v112
	v_sqrt_f32_e32 v113, v113
	v_sqrt_f32_e32 v114, v114
	v_sqrt_f32_e32 v115, v115
	v_mul_f32_e32 v100, v100, v112
	v_mul_f32_e32 v101, v101, v113
	v_mul_f32_e32 v102, v102, v114
	v_mul_f32_e32 v103, v103, v115
	v_mul_f32_e32 v112, v228, v100
	v_mul_f32_e32 v113, v229, v101
	v_mul_f32_e32 v114, v230, v102
	v_mul_f32_e32 v115, v231, v103
	s_cmp_eq_u64 s[16:17], exec
	s_cbranch_scc1 .Lgp_nomask_dir1_0
	v_cndmask_b32_e64 v112, 0, v112, s[16:17]
	v_cndmask_b32_e64 v113, 0, v113, s[16:17]
	v_cndmask_b32_e64 v114, 0, v114, s[16:17]
	v_cndmask_b32_e64 v115, 0, v115, s[16:17]
	v_cndmask_b32_e64 v96, 1.0, v96, s[16:17]
	v_cndmask_b32_e64 v97, 1.0, v97, s[16:17]
	v_cndmask_b32_e64 v98, 1.0, v98, s[16:17]
	v_cndmask_b32_e64 v99, 1.0, v99, s[16:17]
.Lgp_nomask_dir1_0:
	ds_write_b128 v224, v[96:99] offset:6784
	ds_write_b128 v224, v[112:115] offset:10880
	ds_read_b128 v[96:99], v134
	ds_read_b128 v[100:103], v135
	ds_read_b128 v[104:107], v117 offset:12288
	ds_read_b128 v[228:231], v117 offset:13312
	v_exp_f32_e32 v232, v232
	v_exp_f32_e32 v233, v233
	v_exp_f32_e32 v234, v234
	v_exp_f32_e32 v235, v235
	v_exp_f32_e32 v236, v236
	v_exp_f32_e32 v237, v237
	v_exp_f32_e32 v238, v238
	v_exp_f32_e32 v239, v239
	v_add_f32_e32 v232, 1.0, v232
	v_add_f32_e32 v233, 1.0, v233
	v_add_f32_e32 v234, 1.0, v234
	v_add_f32_e32 v235, 1.0, v235
	v_add_f32_e32 v236, 1.0, v236
	v_add_f32_e32 v237, 1.0, v237
	v_add_f32_e32 v238, 1.0, v238
	v_add_f32_e32 v239, 1.0, v239
	v_rcp_f32_e32 v232, v232
	v_rcp_f32_e32 v233, v233
	v_rcp_f32_e32 v234, v234
	v_rcp_f32_e32 v235, v235
	v_rcp_f32_e32 v236, v236
	v_rcp_f32_e32 v237, v237
	v_rcp_f32_e32 v238, v238
	v_rcp_f32_e32 v239, v239
	s_waitcnt lgkmcnt(0)
	v_mfma_f32_16x16x32_bf16 v[96:99], v[60:63], v[88:91], v[96:99]
	v_mfma_f32_16x16x32_bf16 v[100:103], v[104:107], v[88:91], v[100:103]
	v_mfma_f32_16x16x32_bf16 v[96:99], v[64:67], v[92:95], v[96:99]
	v_mfma_f32_16x16x32_bf16 v[100:103], v[228:231], v[92:95], v[100:103]
	ds_read_b128 v[104:107], v136
	ds_read_b128 v[228:231], v128 offset:2560
	v_mul_f32_e32 v232, v232, v240
	v_mul_f32_e32 v233, v233, v241
	v_mul_f32_e32 v234, v234, v242
	v_mul_f32_e32 v235, v235, v243
	v_exp_f32_e32 v232, v232
	v_exp_f32_e32 v233, v233
	v_exp_f32_e32 v234, v234
	v_exp_f32_e32 v235, v235
	v_fma_f32 v112, -v232, v232, 1.0
	v_fma_f32 v113, -v233, v233, 1.0
	v_fma_f32 v114, -v234, v234, 1.0
	v_fma_f32 v115, -v235, v235, 1.0
	v_max_f32_e32 v112, 0, v112
	v_max_f32_e32 v113, 0, v113
	v_max_f32_e32 v114, 0, v114
	v_max_f32_e32 v115, 0, v115
	v_sqrt_f32_e32 v112, v112
	v_sqrt_f32_e32 v113, v113
	v_sqrt_f32_e32 v114, v114
	v_sqrt_f32_e32 v115, v115
	v_mul_f32_e32 v236, v236, v112
	v_mul_f32_e32 v237, v237, v113
	v_mul_f32_e32 v238, v238, v114
	v_mul_f32_e32 v239, v239, v115
	v_mul_f32_e32 v112, v108, v236
	v_mul_f32_e32 v113, v109, v237
	v_mul_f32_e32 v114, v110, v238
	v_mul_f32_e32 v115, v111, v239
	s_cmp_eq_u64 s[16:17], exec
	s_cbranch_scc1 .Lgp_nomask_dir1_1
	v_cndmask_b32_e64 v112, 0, v112, s[16:17]
	v_cndmask_b32_e64 v113, 0, v113, s[16:17]
	v_cndmask_b32_e64 v114, 0, v114, s[16:17]
	v_cndmask_b32_e64 v115, 0, v115, s[16:17]
	v_cndmask_b32_e64 v232, 1.0, v232, s[16:17]
	v_cndmask_b32_e64 v233, 1.0, v233, s[16:17]
	v_cndmask_b32_e64 v234, 1.0, v234, s[16:17]
	v_cndmask_b32_e64 v235, 1.0, v235, s[16:17]
; #define LAS __attribute__((address_space(3)))
; #define MFMA16(a, b, c) __builtin_amdgcn_mfma_f32_16x16x32_bf16((a), (b), (c), 0, 0, 0)
; template <int DIR>
; __device__ __forceinline__ void rnn_scan_unit(const Params& p, LAS unsigned char* lds, int b, int g) {
;     ...
;           for (int n = 0; n < 4; ++n) { const int c4 = 16 * n + 4 * fq;
;               f32x4 ra = *(const LAS f32x4*)(cst + c4), ia = *(const LAS f32x4*)(cst + 64 + c4);
; #pragma unroll
;               for (int ks = 0; ks < 2; ++ks) { ra = MFMA16(wreg[(0 * 4 + n) * 2 + ks], af[ks], ra); ia = MFMA16(wl[((1 * 4 + n) * 2 + ks) * 64 + lane], af[ks], ia); }
;               const f32x4 xv = *(const LAS f32x4*)(xcf + tt * XS + c4);
;               const f32x4 spv = *(const LAS f32x4*)(cst + 128 + c4);
;               f32x4 av, bv;
; #pragma unroll
;               for (int i = 0; i < 4; ++i) { const float r = __builtin_amdgcn_rcpf(1.0f + __builtin_amdgcn_exp2f(ra[i])), ig = __builtin_amdgcn_rcpf(1.0f + __builtin_amdgcn_exp2f(ia[i]));
;                   const float a = __builtin_amdgcn_exp2f(r * spv[i]); const float em = fmaf(-a, a, 1.0f);
;                   av[i] = valid ? a : 1.0f; bv[i] = valid ? __builtin_amdgcn_sqrtf(fmaxf(em, 0.0f)) * ig * xv[i] : 0.0f; }
;               *(LAS f32x4*)(al + tt * 64 + c4) = av; *(LAS f32x4*)(bl + tt * 64 + c4) = bv; } }
.Lgp_nomask_dir1_1:
	ds_write_b128 v225, v[232:235] offset:6784
	ds_write_b128 v225, v[112:115] offset:10880
	ds_read_b128 v[232:235], v137
	ds_read_b128 v[236:239], v138
	ds_read_b128 v[240:243], v117 offset:14336
	ds_read_b128 v[108:111], v117 offset:15360
	v_exp_f32_e32 v96, v96
	v_exp_f32_e32 v97, v97
	v_exp_f32_e32 v98, v98
	v_exp_f32_e32 v99, v99
	v_exp_f32_e32 v100, v100
	v_exp_f32_e32 v101, v101
	v_exp_f32_e32 v102, v102
	v_exp_f32_e32 v103, v103
	v_add_f32_e32 v96, 1.0, v96
	v_add_f32_e32 v97, 1.0, v97
	v_add_f32_e32 v98, 1.0, v98
	v_add_f32_e32 v99, 1.0, v99
	v_add_f32_e32 v100, 1.0, v100
	v_add_f32_e32 v101, 1.0, v101
	v_add_f32_e32 v102, 1.0, v102
	v_add_f32_e32 v103, 1.0, v103
	v_rcp_f32_e32 v96, v96
	v_rcp_f32_e32 v97, v97
	v_rcp_f32_e32 v98, v98
	v_rcp_f32_e32 v99, v99
	v_rcp_f32_e32 v100, v100
	v_rcp_f32_e32 v101, v101
	v_rcp_f32_e32 v102, v102
	v_rcp_f32_e32 v103, v103
	s_waitcnt lgkmcnt(0)
	v_mfma_f32_16x16x32_bf16 v[232:235], v[68:71], v[88:91], v[232:235]
	v_mfma_f32_16x16x32_bf16 v[236:239], v[240:243], v[88:91], v[236:239]
	v_mfma_f32_16x16x32_bf16 v[232:235], v[72:75], v[92:95], v[232:235]
	v_mfma_f32_16x16x32_bf16 v[236:239], v[108:111], v[92:95], v[236:239]
	ds_read_b128 v[240:243], v139
	ds_read_b128 v[108:111], v128 offset:2624
	v_mul_f32_e32 v96, v96, v104
	v_mul_f32_e32 v97, v97, v105
	v_mul_f32_e32 v98, v98, v106
	v_mul_f32_e32 v99, v99, v107
	v_exp_f32_e32 v96, v96
	v_exp_f32_e32 v97, v97
	v_exp_f32_e32 v98, v98
	v_exp_f32_e32 v99, v99
	v_fma_f32 v112, -v96, v96, 1.0
	v_fma_f32 v113, -v97, v97, 1.0
	v_fma_f32 v114, -v98, v98, 1.0
	v_fma_f32 v115, -v99, v99, 1.0
	v_max_f32_e32 v112, 0, v112
	v_max_f32_e32 v113, 0, v113
	v_max_f32_e32 v114, 0, v114
	v_max_f32_e32 v115, 0, v115
	v_sqrt_f32_e32 v112, v112
	v_sqrt_f32_e32 v113, v113
	v_sqrt_f32_e32 v114, v114
	v_sqrt_f32_e32 v115, v115
	v_mul_f32_e32 v100, v100, v112
	v_mul_f32_e32 v101, v101, v113
	v_mul_f32_e32 v102, v102, v114
	v_mul_f32_e32 v103, v103, v115
	v_mul_f32_e32 v112, v228, v100
	v_mul_f32_e32 v113, v229, v101
	v_mul_f32_e32 v114, v230, v102
	v_mul_f32_e32 v115, v231, v103
	s_cmp_eq_u64 s[16:17], exec
	s_cbranch_scc1 .Lgp_nomask_dir1_2
	v_cndmask_b32_e64 v112, 0, v112, s[16:17]
	v_cndmask_b32_e64 v113, 0, v113, s[16:17]
	v_cndmask_b32_e64 v114, 0, v114, s[16:17]
	v_cndmask_b32_e64 v115, 0, v115, s[16:17]
	v_cndmask_b32_e64 v96, 1.0, v96, s[16:17]
	v_cndmask_b32_e64 v97, 1.0, v97, s[16:17]
	v_cndmask_b32_e64 v98, 1.0, v98, s[16:17]
	v_cndmask_b32_e64 v99, 1.0, v99, s[16:17]
.Lgp_nomask_dir1_2:
	ds_write_b128 v226, v[96:99] offset:6784
	ds_write_b128 v226, v[112:115] offset:10880
	v_exp_f32_e32 v232, v232
	v_exp_f32_e32 v233, v233
	v_exp_f32_e32 v234, v234
	v_exp_f32_e32 v235, v235
	v_exp_f32_e32 v236, v236
	v_exp_f32_e32 v237, v237
	v_exp_f32_e32 v238, v238
	v_exp_f32_e32 v239, v239
	v_add_f32_e32 v232, 1.0, v232
	v_add_f32_e32 v233, 1.0, v233
	v_add_f32_e32 v234, 1.0, v234
	v_add_f32_e32 v235, 1.0, v235
	v_add_f32_e32 v236, 1.0, v236
	v_add_f32_e32 v237, 1.0, v237
	v_add_f32_e32 v238, 1.0, v238
	v_add_f32_e32 v239, 1.0, v239
	v_rcp_f32_e32 v232, v232
	v_rcp_f32_e32 v233, v233
	v_rcp_f32_e32 v234, v234
	v_rcp_f32_e32 v235, v235
	v_rcp_f32_e32 v236, v236
	v_rcp_f32_e32 v237, v237
	v_rcp_f32_e32 v238, v238
	v_rcp_f32_e32 v239, v239
	s_waitcnt lgkmcnt(0)
	v_mul_f32_e32 v232, v232, v240
	v_mul_f32_e32 v233, v233, v241
	v_mul_f32_e32 v234, v234, v242
	v_mul_f32_e32 v235, v235, v243
	v_exp_f32_e32 v232, v232
	v_exp_f32_e32 v233, v233
	v_exp_f32_e32 v234, v234
	v_exp_f32_e32 v235, v235
	v_fma_f32 v112, -v232, v232, 1.0
	v_fma_f32 v113, -v233, v233, 1.0
	v_fma_f32 v114, -v234, v234, 1.0
	v_fma_f32 v115, -v235, v235, 1.0
	v_max_f32_e32 v112, 0, v112
	v_max_f32_e32 v113, 0, v113
	v_max_f32_e32 v114, 0, v114
	v_max_f32_e32 v115, 0, v115
	v_sqrt_f32_e32 v112, v112
	v_sqrt_f32_e32 v113, v113
	v_sqrt_f32_e32 v114, v114
	v_sqrt_f32_e32 v115, v115
	v_mul_f32_e32 v236, v236, v112
	v_mul_f32_e32 v237, v237, v113
	v_mul_f32_e32 v238, v238, v114
	v_mul_f32_e32 v239, v239, v115
	v_mul_f32_e32 v112, v108, v236
	v_mul_f32_e32 v113, v109, v237
	v_mul_f32_e32 v114, v110, v238
	v_mul_f32_e32 v115, v111, v239
	s_cmp_eq_u64 s[16:17], exec
	s_cbranch_scc1 .Lgp_nomask_dir1_3
	v_cndmask_b32_e64 v112, 0, v112, s[16:17]
	v_cndmask_b32_e64 v113, 0, v113, s[16:17]
	v_cndmask_b32_e64 v114, 0, v114, s[16:17]
	v_cndmask_b32_e64 v115, 0, v115, s[16:17]
	v_cndmask_b32_e64 v232, 1.0, v232, s[16:17]
	v_cndmask_b32_e64 v233, 1.0, v233, s[16:17]
	v_cndmask_b32_e64 v234, 1.0, v234, s[16:17]
	v_cndmask_b32_e64 v235, 1.0, v235, s[16:17]
; #define LAS __attribute__((address_space(3)))
; __device__ __forceinline__ unsigned cvt_pk(float lo, float hi) { unsigned r; asm("v_cvt_pk_bf16_f32 %0, %1, %2" : "=v"(r) : "v"(lo), "v"(hi)); return r; }
; #define LDS_BARRIER() asm volatile("s_waitcnt lgkmcnt(0)\n\ts_barrier" ::: "memory")
; template <int DIR>
; __device__ __forceinline__ void rnn_scan_unit(const Params& p, LAS unsigned char* lds, int b, int g) {
;     ...
;               *(LAS f32x4*)(al + tt * 64 + c4) = av; *(LAS f32x4*)(bl + tt * 64 + c4) = bv; } }
;         asm volatile("s_waitcnt lgkmcnt(0)" ::: "memory");
;         LAS float* sgA = sg + (ci & 1) * 1024; LAS float* sgB = sgA + 512;
;         float av_[16], bv_[16];
;         { float A = 1.f, B = 0.f;
; #pragma unroll
;           for (int k = 0; k < 16; ++k) { const int tt = DIR == 0 ? k : 15 - k; av_[k] = al[tt * 64 + ch]; bv_[k] = bl[tt * 64 + ch]; B = av_[k] * B + bv_[k]; A *= av_[k]; }
;           sgA[seg * 64 + ch] = A; sgB[seg * 64 + ch] = B; }
;         LDS_BARRIER();
;         float h = hcar, hin = hcar;
; #pragma unroll
;         for (int s = 0; s < 8; ++s) { const int sx = DIR == 0 ? s : 7 - s; hin = (sx == seg) ? h : hin; h = sgA[sx * 64 + ch] * h + sgB[sx * 64 + ch]; }
;         hcar = h;
; #pragma unroll
;         for (int k = 0; k < 16; ++k) { const int tt = DIR == 0 ? k : 15 - k; hin = av_[k] * hin + bv_[k]; bl[tt * 64 + ch] = hin; }
;         asm volatile("s_waitcnt lgkmcnt(0)" ::: "memory");
;         { const int tk = lane >> 2, cq4 = lane & 3;
;           if (t0 + tk < TT) { const LAS float* src = bl + tk * 64 + 16 * cq4;
;               const f32x4 x0 = *(const LAS f32x4*)(src), x1 = *(const LAS f32x4*)(src + 4), x2 = *(const LAS f32x4*)(src + 8), x3 = *(const LAS f32x4*)(src + 12);
;               u32x4 w0, w1; w0.x = cvt_pk(x0[0], x0[1]); w0.y = cvt_pk(x0[2], x0[3]); w0.z = cvt_pk(x1[0], x1[1]); w0.w = cvt_pk(x1[2], x1[3]);
;               w1.x = cvt_pk(x2[0], x2[1]); w1.y = cvt_pk(x2[2], x2[3]); w1.z = cvt_pk(x3[0], x3[1]); w1.w = cvt_pk(x3[2], x3[3]);
;               bf16_t* hp = H + ((size_t)b * TT + t0 + tk) * 512 + 64 * g + 16 * cq4;
;               *(u32x4*)hp = w0; *(u32x4*)(hp + 8) = w1; } }
.Lgp_nomask_dir1_3:
	ds_write_b128 v227, v[232:235] offset:6784
	ds_write_b128 v227, v[112:115] offset:10880
	s_waitcnt lgkmcnt(0)
	ds_read2st64_b32 v[194:195], v219 offset0:33 offset1:41
	ds_read2st64_b32 v[210:211], v219 offset0:49 offset1:57
	ds_read2st64_b32 v[192:193], v218 offset0:32 offset1:40
	ds_read2st64_b32 v[208:209], v218 offset0:48 offset1:56
	ds_read2st64_b32 v[190:191], v217 offset0:31 offset1:39
	ds_read2st64_b32 v[206:207], v217 offset0:47 offset1:55
	ds_read2st64_b32 v[188:189], v216 offset0:30 offset1:38
	ds_read2st64_b32 v[204:205], v216 offset0:46 offset1:54
	ds_read2st64_b32 v[186:187], v215 offset0:29 offset1:37
	ds_read2st64_b32 v[202:203], v215 offset0:45 offset1:53
	ds_read2st64_b32 v[184:185], v214 offset0:28 offset1:36
	ds_read2st64_b32 v[200:201], v214 offset0:44 offset1:52
	ds_read2st64_b32 v[182:183], v213 offset0:27 offset1:35
	ds_read2st64_b32 v[198:199], v213 offset0:43 offset1:51
	ds_read2st64_b32 v[180:181], v212 offset0:26 offset1:34
	ds_read2st64_b32 v[196:197], v212 offset0:42 offset1:50
	s_and_b32 s16, s34, 0x400
	s_lshl_b32 s16, s16, 2
	s_add_i32 s16, s16, 0
	s_add_i32 s16, s16, 0x1d400
	v_lshl_add_u32 v110, v116, 2, s16
	s_waitcnt lgkmcnt(14)
	v_fma_f32 v0, 0, v195, v211
	s_waitcnt lgkmcnt(12)
	v_fma_f32 v0, v0, v193, v209
	v_mul_f32_e32 v3, v195, v193
	s_waitcnt lgkmcnt(10)
	v_fma_f32 v0, v0, v191, v207
	v_mul_f32_e32 v3, v3, v191
	s_waitcnt lgkmcnt(8)
	v_fma_f32 v0, v0, v189, v205
	v_mul_f32_e32 v3, v3, v189
	s_waitcnt lgkmcnt(6)
	v_fma_f32 v0, v0, v187, v203
	v_mul_f32_e32 v3, v3, v187
	s_waitcnt lgkmcnt(4)
	v_fma_f32 v0, v0, v185, v201
	v_mul_f32_e32 v3, v3, v185
	s_waitcnt lgkmcnt(2)
	v_fma_f32 v0, v0, v183, v199
	v_mul_f32_e32 v3, v3, v183
	s_waitcnt lgkmcnt(0)
	v_fma_f32 v0, v0, v181, v197
	v_mul_f32_e32 v3, v3, v181
	v_fma_f32 v0, v0, v194, v210
	v_mul_f32_e32 v3, v3, v194
	v_fma_f32 v0, v0, v192, v208
	v_mul_f32_e32 v3, v3, v192
	v_fma_f32 v0, v0, v190, v206
	v_mul_f32_e32 v3, v3, v190
	v_fma_f32 v0, v0, v188, v204
	v_mul_f32_e32 v3, v3, v188
	v_fma_f32 v0, v0, v186, v202
	v_mul_f32_e32 v3, v3, v186
	v_fma_f32 v0, v0, v184, v200
	v_mul_f32_e32 v3, v3, v184
	v_fma_f32 v0, v0, v182, v198
	v_mul_f32_e32 v3, v3, v182
	v_fma_f32 v0, v0, v180, v196
	v_mul_f32_e32 v3, v3, v180
	ds_write2st64_b32 v110, v3, v0 offset1:8
	s_waitcnt lgkmcnt(0)
	s_barrier
	v_lshl_add_u32 v0, v122, 2, s16
	ds_read2st64_b32 v[110:111], v0 offset0:6 offset1:7
	ds_read2st64_b32 v[176:177], v0 offset0:14 offset1:15
	s_waitcnt lgkmcnt(0)
	v_fma_f32 v3, v2, v111, v177
	v_cndmask_b32_e64 v2, v2, v3, s[0:1]
	v_fmac_f32_e32 v176, v3, v110
	v_cndmask_b32_e64 v177, v2, v176, s[2:3]
	ds_read2st64_b32 v[2:3], v0 offset0:4 offset1:5
	ds_read2st64_b32 v[110:111], v0 offset0:12 offset1:13
	s_waitcnt lgkmcnt(0)
	v_fma_f32 v3, v176, v3, v111
	v_cndmask_b32_e64 v111, v177, v3, s[4:5]
	v_fmac_f32_e32 v110, v3, v2
	ds_read2st64_b32 v[2:3], v0 offset0:2 offset1:3
	ds_read2st64_b32 v[176:177], v0 offset0:10 offset1:11
	v_cndmask_b32_e64 v111, v111, v110, s[8:9]
	s_waitcnt lgkmcnt(0)
	v_fma_f32 v3, v110, v3, v177
	v_cndmask_b32_e64 v110, v111, v3, s[10:11]
	v_fmac_f32_e32 v176, v3, v2
	v_cndmask_b32_e64 v177, v110, v176, s[12:13]
	ds_read2st64_b32 v[110:111], v0 offset1:1
	ds_read2st64_b32 v[2:3], v0 offset0:8 offset1:9
	s_waitcnt lgkmcnt(0)
	v_fma_f32 v0, v176, v111, v3
	v_cndmask_b32_e64 v3, v177, v0, s[14:15]
	v_fma_f32 v211, v195, v3, v211
	v_fma_f32 v209, v193, v211, v209
	v_fma_f32 v207, v191, v209, v207
	v_fma_f32 v205, v189, v207, v205
	v_fma_f32 v203, v187, v205, v203
	v_fma_f32 v201, v185, v203, v201
	v_fma_f32 v199, v183, v201, v199
	v_fma_f32 v197, v181, v199, v197
	v_fma_f32 v210, v194, v197, v210
	ds_write2st64_b32 v219, v210, v211 offset0:49 offset1:57
	v_fma_f32 v208, v192, v210, v208
	ds_write2st64_b32 v218, v208, v209 offset0:48 offset1:56
	v_fma_f32 v206, v190, v208, v206
	ds_write2st64_b32 v217, v206, v207 offset0:47 offset1:55
	v_fma_f32 v204, v188, v206, v204
	ds_write2st64_b32 v216, v204, v205 offset0:46 offset1:54
	v_fma_f32 v202, v186, v204, v202
	ds_write2st64_b32 v215, v202, v203 offset0:45 offset1:53
	v_fma_f32 v200, v184, v202, v200
	ds_write2st64_b32 v214, v200, v201 offset0:44 offset1:52
	v_fma_f32 v198, v182, v200, v198
	ds_write2st64_b32 v213, v198, v199 offset0:43 offset1:51
	v_fma_f32 v196, v180, v198, v196
	ds_write2st64_b32 v212, v196, v197 offset0:42 offset1:50
	s_waitcnt lgkmcnt(0)
	v_add_u32_e32 v3, s19, v159
	v_cmp_gt_i32_e64 s[16:17], s86, v3
	s_waitcnt vmcnt(0)
	s_and_saveexec_b64 s[76:77], s[16:17]
	s_cbranch_execz .LBB0_539
	ds_read_b128 v[88:91], v220 offset:10880
	ds_read_b128 v[92:95], v221 offset:10880
	ds_read_b128 v[96:99], v222 offset:10880
	ds_read_b128 v[100:103], v223 offset:10880
	s_waitcnt lgkmcnt(3)
	v_cvt_pk_bf16_f32 v88, v88, v89
	v_cvt_pk_bf16_f32 v89, v90, v91
	s_waitcnt lgkmcnt(2)
	v_cvt_pk_bf16_f32 v90, v92, v93
	v_cvt_pk_bf16_f32 v91, v94, v95
	s_waitcnt lgkmcnt(1)
	v_cvt_pk_bf16_f32 v92, v96, v97
	v_cvt_pk_bf16_f32 v93, v98, v99
	s_waitcnt lgkmcnt(0)
	v_cvt_pk_bf16_f32 v94, v100, v101
	v_cvt_pk_bf16_f32 v95, v102, v103
	global_store_dwordx4 v[120:121], v[88:91], off
	global_store_dwordx4 v[120:121], v[92:95], off offset:16
	s_branch .LBB0_539

; #define LAS __attribute__((address_space(3)))
; __device__ __forceinline__ unsigned cvt_pk(float lo, float hi) { unsigned r; asm("v_cvt_pk_bf16_f32 %0, %1, %2" : "=v"(r) : "v"(lo), "v"(hi)); return r; }
; __device__ __forceinline__ float bflo(unsigned w) { return __uint_as_float(w << 16); }
; __device__ __forceinline__ float bfhi(unsigned w) { return __uint_as_float(w & 0xffff0000u); }
; #define MFMA16(a, b, c) __builtin_amdgcn_mfma_f32_16x16x32_bf16((a), (b), (c), 0, 0, 0)
; template <int DIR>
; __device__ __forceinline__ void rnn_scan_unit(const Params& p, LAS unsigned char* lds, int b, int g) {
;     ...
;         { const int tl0 = lane >> 3, c8 = lane & 7;
; #pragma unroll
;           for (int hh = 0; hh < 2; ++hh) { const int tl = tl0 + 8 * hh;
;               f32x4 o0 = cbv[0], o1 = cbv[1];
; #pragma unroll
;               for (int j = 0; j < 4; ++j) { const u32x4 xw_ = *(const LAS u32x4*)(xrb + (tl + j) * 64 + 8 * c8);
;                   o0[0] += cwv[j][0][0] * bflo(xw_.x); o0[1] += cwv[j][0][1] * bfhi(xw_.x); o0[2] += cwv[j][0][2] * bflo(xw_.y); o0[3] += cwv[j][0][3] * bfhi(xw_.y);
;                   o1[0] += cwv[j][1][0] * bflo(xw_.z); o1[1] += cwv[j][1][1] * bfhi(xw_.z); o1[2] += cwv[j][1][2] * bflo(xw_.w); o1[3] += cwv[j][1][3] * bfhi(xw_.w); }
;               *(LAS f32x4*)(xcf + tl * XS + 8 * c8) = o0; *(LAS f32x4*)(xcf + tl * XS + 8 * c8 + 4) = o1; } }
;         asm volatile("s_waitcnt lgkmcnt(0)" ::: "memory");
;         { const int tt = fr; const bool valid = (t0 + tt) < TT;
;           bf16x8 af[2];
; #pragma unroll
;           for (int ks = 0; ks < 2; ++ks) { const f32x4 x0 = *(const LAS f32x4*)(xcf + tt * XS + 32 * ks + 8 * fq), x1 = *(const LAS f32x4*)(xcf + tt * XS + 32 * ks + 8 * fq + 4);
;               u32x4 w; w.x = cvt_pk(x0[0], x0[1]); w.y = cvt_pk(x0[2], x0[3]); w.z = cvt_pk(x1[0], x1[1]); w.w = cvt_pk(x1[2], x1[3]); af[ks] = __builtin_bit_cast(bf16x8, w); }
; #pragma unroll
;           for (int n = 0; n < 4; ++n) { const int c4 = 16 * n + 4 * fq;
;               f32x4 ra = *(const LAS f32x4*)(cst + c4), ia = *(const LAS f32x4*)(cst + 64 + c4);
; #pragma unroll
;               for (int ks = 0; ks < 2; ++ks) { ra = MFMA16(wreg[(0 * 4 + n) * 2 + ks], af[ks], ra); ia = MFMA16(wl[((1 * 4 + n) * 2 + ks) * 64 + lane], af[ks], ia); }
.LBB0_606:
	v_add_u32_e32 v0, v123, v126
	ds_read_b128 v[88:91], v0
	ds_read_b128 v[92:95], v0 offset:128
	ds_read_b128 v[96:99], v0 offset:256
	ds_read_b128 v[100:103], v0 offset:384
	v_mov_b32_e32 v113, 0
	s_waitcnt lgkmcnt(3)
	v_lshlrev_b32_e32 v104, 16, v88
	v_and_b32_e32 v105, 0xffff0000, v88
	v_lshlrev_b32_e32 v88, 16, v89
	v_and_b32_e32 v89, 0xffff0000, v89
	v_pk_fma_f32 v[104:105], v[36:37], v[104:105], v[40:41]
	s_waitcnt lgkmcnt(2)
	v_lshlrev_b32_e32 v106, 16, v92
	v_and_b32_e32 v107, 0xffff0000, v92
	v_pk_fma_f32 v[88:89], v[38:39], v[88:89], v[42:43]
	v_lshlrev_b32_e32 v92, 16, v93
	v_and_b32_e32 v93, 0xffff0000, v93
	v_pk_fma_f32 v[104:105], v[8:9], v[106:107], v[104:105]
	s_waitcnt lgkmcnt(1)
	v_lshlrev_b32_e32 v106, 16, v96
	v_and_b32_e32 v107, 0xffff0000, v96
	v_pk_fma_f32 v[88:89], v[10:11], v[92:93], v[88:89]
	v_lshlrev_b32_e32 v92, 16, v97
	v_and_b32_e32 v93, 0xffff0000, v97
	v_pk_fma_f32 v[104:105], v[12:13], v[106:107], v[104:105]
	s_waitcnt lgkmcnt(0)
	v_lshlrev_b32_e32 v106, 16, v100
	v_and_b32_e32 v107, 0xffff0000, v100
	v_pk_fma_f32 v[88:89], v[14:15], v[92:93], v[88:89]
	v_lshlrev_b32_e32 v92, 16, v101
	v_and_b32_e32 v93, 0xffff0000, v101
	v_pk_fma_f32 v[104:105], v[20:21], v[106:107], v[104:105]
	v_pk_fma_f32 v[106:107], v[22:23], v[92:93], v[88:89]
	v_lshlrev_b32_e32 v88, 16, v90
	v_and_b32_e32 v89, 0xffff0000, v90
	v_pk_fma_f32 v[88:89], v[28:29], v[88:89], v[32:33]
	v_lshlrev_b32_e32 v92, 16, v94
	v_and_b32_e32 v93, 0xffff0000, v94
	v_pk_fma_f32 v[88:89], v[4:5], v[92:93], v[88:89]
	v_lshlrev_b32_e32 v92, 16, v98
	v_and_b32_e32 v93, 0xffff0000, v98
	v_pk_fma_f32 v[88:89], v[16:17], v[92:93], v[88:89]
	v_lshlrev_b32_e32 v92, 16, v102
	v_and_b32_e32 v93, 0xffff0000, v102
	v_lshlrev_b32_e32 v90, 16, v91
	v_and_b32_e32 v91, 0xffff0000, v91
	v_pk_fma_f32 v[88:89], v[24:25], v[92:93], v[88:89]
	v_pk_fma_f32 v[90:91], v[30:31], v[90:91], v[34:35]
	v_lshlrev_b32_e32 v92, 16, v95
	v_and_b32_e32 v93, 0xffff0000, v95
	v_pk_fma_f32 v[90:91], v[6:7], v[92:93], v[90:91]
	v_lshlrev_b32_e32 v92, 16, v99
	v_and_b32_e32 v93, 0xffff0000, v99
	v_pk_fma_f32 v[90:91], v[18:19], v[92:93], v[90:91]
	v_lshlrev_b32_e32 v92, 16, v103
	v_and_b32_e32 v93, 0xffff0000, v103
	v_pk_fma_f32 v[90:91], v[26:27], v[92:93], v[90:91]
	ds_write_b128 v165, v[104:107] offset:2432
	ds_write_b128 v165, v[88:91] offset:2448
	ds_read_b128 v[88:91], v166
	ds_read_b128 v[92:95], v0 offset:1152
	ds_read_b128 v[96:99], v0 offset:1280
	ds_read_b128 v[100:103], v0 offset:1408
	v_add_u32_e32 v0, s19, v159
	s_waitcnt lgkmcnt(3)
	v_lshlrev_b32_e32 v104, 16, v88
	v_and_b32_e32 v105, 0xffff0000, v88
	v_lshlrev_b32_e32 v88, 16, v89
	v_and_b32_e32 v89, 0xffff0000, v89
	v_pk_fma_f32 v[104:105], v[36:37], v[104:105], v[40:41]
	s_waitcnt lgkmcnt(2)
	v_lshlrev_b32_e32 v106, 16, v92
	v_and_b32_e32 v107, 0xffff0000, v92
	v_pk_fma_f32 v[88:89], v[38:39], v[88:89], v[42:43]
	v_lshlrev_b32_e32 v92, 16, v93
	v_and_b32_e32 v93, 0xffff0000, v93
	v_pk_fma_f32 v[104:105], v[8:9], v[106:107], v[104:105]
	s_waitcnt lgkmcnt(1)
	v_lshlrev_b32_e32 v106, 16, v96
	v_and_b32_e32 v107, 0xffff0000, v96
	v_pk_fma_f32 v[88:89], v[10:11], v[92:93], v[88:89]
	v_lshlrev_b32_e32 v92, 16, v97
	v_and_b32_e32 v93, 0xffff0000, v97
	v_pk_fma_f32 v[104:105], v[12:13], v[106:107], v[104:105]
	s_waitcnt lgkmcnt(0)
	v_lshlrev_b32_e32 v106, 16, v100
	v_and_b32_e32 v107, 0xffff0000, v100
	v_pk_fma_f32 v[88:89], v[14:15], v[92:93], v[88:89]
	v_lshlrev_b32_e32 v92, 16, v101
	v_and_b32_e32 v93, 0xffff0000, v101
	v_pk_fma_f32 v[104:105], v[20:21], v[106:107], v[104:105]
	v_pk_fma_f32 v[106:107], v[22:23], v[92:93], v[88:89]
	v_lshlrev_b32_e32 v88, 16, v90
	v_and_b32_e32 v89, 0xffff0000, v90
	v_pk_fma_f32 v[88:89], v[28:29], v[88:89], v[32:33]
	v_lshlrev_b32_e32 v92, 16, v94
	v_and_b32_e32 v93, 0xffff0000, v94
	v_pk_fma_f32 v[88:89], v[4:5], v[92:93], v[88:89]
	v_lshlrev_b32_e32 v92, 16, v98
	v_and_b32_e32 v93, 0xffff0000, v98
	v_pk_fma_f32 v[88:89], v[16:17], v[92:93], v[88:89]
	v_lshlrev_b32_e32 v92, 16, v102
	v_and_b32_e32 v93, 0xffff0000, v102
	v_lshlrev_b32_e32 v90, 16, v91
	v_and_b32_e32 v91, 0xffff0000, v91
	v_pk_fma_f32 v[88:89], v[24:25], v[92:93], v[88:89]
	v_pk_fma_f32 v[90:91], v[30:31], v[90:91], v[34:35]
	v_lshlrev_b32_e32 v92, 16, v95
	v_and_b32_e32 v93, 0xffff0000, v95
	v_pk_fma_f32 v[90:91], v[6:7], v[92:93], v[90:91]
	v_lshlrev_b32_e32 v92, 16, v99
	v_and_b32_e32 v93, 0xffff0000, v99
	v_pk_fma_f32 v[90:91], v[18:19], v[92:93], v[90:91]
	v_lshlrev_b32_e32 v92, 16, v103
	v_and_b32_e32 v93, 0xffff0000, v103
	v_pk_fma_f32 v[90:91], v[26:27], v[92:93], v[90:91]
	ds_write_b128 v165, v[104:107] offset:4608
	ds_write_b128 v165, v[88:91] offset:4624
	s_waitcnt lgkmcnt(0)
	ds_read_b128 v[88:91], v167 offset:2432
	ds_read_b128 v[92:95], v167 offset:2448
	s_waitcnt lgkmcnt(1)
	v_cvt_pk_bf16_f32 v88, v88, v89
	v_cvt_pk_bf16_f32 v89, v90, v91
	s_waitcnt lgkmcnt(0)
	v_cvt_pk_bf16_f32 v90, v92, v93
	v_cvt_pk_bf16_f32 v91, v94, v95
	ds_read_b128 v[92:95], v167 offset:2560
	ds_read_b128 v[96:99], v167 offset:2576
	s_waitcnt lgkmcnt(1)
	v_cvt_pk_bf16_f32 v92, v92, v93
	v_cvt_pk_bf16_f32 v93, v94, v95
	s_waitcnt lgkmcnt(0)
	v_cvt_pk_bf16_f32 v94, v96, v97
	v_cvt_pk_bf16_f32 v95, v98, v99
	ds_read_b128 v[96:99], v127
	ds_read_b128 v[100:103], v128
	ds_read_b128 v[104:107], v122 offset:8192
	ds_read_b128 v[228:231], v122 offset:9216
	v_cmp_gt_i32_e64 s[16:17], s86, v0
	ds_read_b128 v[232:235], v132
	ds_read_b128 v[236:239], v133
	ds_read_b128 v[240:243], v122 offset:10240
	ds_read_b128 v[108:111], v122 offset:11264
	s_waitcnt lgkmcnt(4)
; #define LAS __attribute__((address_space(3)))
; #define MFMA16(a, b, c) __builtin_amdgcn_mfma_f32_16x16x32_bf16((a), (b), (c), 0, 0, 0)
; template <int DIR>
; __device__ __forceinline__ void rnn_scan_unit(const Params& p, LAS unsigned char* lds, int b, int g) {
;     ...
;           for (int n = 0; n < 4; ++n) { const int c4 = 16 * n + 4 * fq;
;               f32x4 ra = *(const LAS f32x4*)(cst + c4), ia = *(const LAS f32x4*)(cst + 64 + c4);
; #pragma unroll
;               for (int ks = 0; ks < 2; ++ks) { ra = MFMA16(wreg[(0 * 4 + n) * 2 + ks], af[ks], ra); ia = MFMA16(wl[((1 * 4 + n) * 2 + ks) * 64 + lane], af[ks], ia); }
;               const f32x4 xv = *(const LAS f32x4*)(xcf + tt * XS + c4);
;               const f32x4 spv = *(const LAS f32x4*)(cst + 128 + c4);
;               f32x4 av, bv;
; #pragma unroll
;               for (int i = 0; i < 4; ++i) { const float r = __builtin_amdgcn_rcpf(1.0f + __builtin_amdgcn_exp2f(ra[i])), ig = __builtin_amdgcn_rcpf(1.0f + __builtin_amdgcn_exp2f(ia[i]));
;                   const float a = __builtin_amdgcn_exp2f(r * spv[i]); const float em = fmaf(-a, a, 1.0f);
;                   av[i] = valid ? a : 1.0f; bv[i] = valid ? __builtin_amdgcn_sqrtf(fmaxf(em, 0.0f)) * ig * xv[i] : 0.0f; }
;               *(LAS f32x4*)(al + tt * 64 + c4) = av; *(LAS f32x4*)(bl + tt * 64 + c4) = bv; } }
	v_mfma_f32_16x16x32_bf16 v[96:99], v[44:47], v[88:91], v[96:99]
	v_mfma_f32_16x16x32_bf16 v[100:103], v[104:107], v[88:91], v[100:103]
	v_mfma_f32_16x16x32_bf16 v[96:99], v[48:51], v[92:95], v[96:99]
	v_mfma_f32_16x16x32_bf16 v[100:103], v[228:231], v[92:95], v[100:103]
	ds_read_b128 v[104:107], v130
	ds_read_b128 v[228:231], v129 offset:2432
	s_nop 7
	v_exp_f32_e32 v96, v96
	v_exp_f32_e32 v97, v97
	v_exp_f32_e32 v98, v98
	v_exp_f32_e32 v99, v99
	v_exp_f32_e32 v100, v100
	v_exp_f32_e32 v101, v101
	v_exp_f32_e32 v102, v102
	v_exp_f32_e32 v103, v103
	v_add_f32_e32 v96, 1.0, v96
	v_add_f32_e32 v97, 1.0, v97
	v_add_f32_e32 v98, 1.0, v98
	v_add_f32_e32 v99, 1.0, v99
	v_add_f32_e32 v100, 1.0, v100
	v_add_f32_e32 v101, 1.0, v101
	v_add_f32_e32 v102, 1.0, v102
	v_add_f32_e32 v103, 1.0, v103
	v_rcp_f32_e32 v96, v96
	v_rcp_f32_e32 v97, v97
	v_rcp_f32_e32 v98, v98
	v_rcp_f32_e32 v99, v99
	v_rcp_f32_e32 v100, v100
	v_rcp_f32_e32 v101, v101
	v_rcp_f32_e32 v102, v102
	v_rcp_f32_e32 v103, v103
	s_waitcnt lgkmcnt(0)
	v_mfma_f32_16x16x32_bf16 v[232:235], v[52:55], v[88:91], v[232:235]
	v_mfma_f32_16x16x32_bf16 v[236:239], v[240:243], v[88:91], v[236:239]
	v_mfma_f32_16x16x32_bf16 v[232:235], v[56:59], v[92:95], v[232:235]
	v_mfma_f32_16x16x32_bf16 v[236:239], v[108:111], v[92:95], v[236:239]
	ds_read_b128 v[240:243], v134
	ds_read_b128 v[108:111], v129 offset:2496
	v_mul_f32_e32 v96, v96, v104
	v_mul_f32_e32 v97, v97, v105
	v_mul_f32_e32 v98, v98, v106
	v_mul_f32_e32 v99, v99, v107
	v_exp_f32_e32 v96, v96
	v_exp_f32_e32 v97, v97
	v_exp_f32_e32 v98, v98
	v_exp_f32_e32 v99, v99
	v_fma_f32 v112, -v96, v96, 1.0
	v_fma_f32 v113, -v97, v97, 1.0
	v_fma_f32 v114, -v98, v98, 1.0
	v_fma_f32 v115, -v99, v99, 1.0
	v_max_f32_e32 v112, 0, v112
	v_max_f32_e32 v113, 0, v113
	v_max_f32_e32 v114, 0, v114
	v_max_f32_e32 v115, 0, v115
	v_sqrt_f32_e32 v112, v112
	v_sqrt_f32_e32 v113, v113
	v_sqrt_f32_e32 v114, v114
	v_sqrt_f32_e32 v115, v115
	v_mul_f32_e32 v100, v100, v112
	v_mul_f32_e32 v101, v101, v113
	v_mul_f32_e32 v102, v102, v114
	v_mul_f32_e32 v103, v103, v115
	v_mul_f32_e32 v112, v228, v100
	v_mul_f32_e32 v113, v229, v101
	v_mul_f32_e32 v114, v230, v102
	v_mul_f32_e32 v115, v231, v103
	s_cmp_eq_u64 s[16:17], exec
	s_cbranch_scc1 .Lgp_nomask_dir0_0
	v_cndmask_b32_e64 v112, 0, v112, s[16:17]
	v_cndmask_b32_e64 v113, 0, v113, s[16:17]
	v_cndmask_b32_e64 v114, 0, v114, s[16:17]
	v_cndmask_b32_e64 v115, 0, v115, s[16:17]
	v_cndmask_b32_e64 v96, 1.0, v96, s[16:17]
	v_cndmask_b32_e64 v97, 1.0, v97, s[16:17]
	v_cndmask_b32_e64 v98, 1.0, v98, s[16:17]
	v_cndmask_b32_e64 v99, 1.0, v99, s[16:17]
; #define LAS __attribute__((address_space(3)))
; #define MFMA16(a, b, c) __builtin_amdgcn_mfma_f32_16x16x32_bf16((a), (b), (c), 0, 0, 0)
; template <int DIR>
; __device__ __forceinline__ void rnn_scan_unit(const Params& p, LAS unsigned char* lds, int b, int g) {
;     ...
;           for (int n = 0; n < 4; ++n) { const int c4 = 16 * n + 4 * fq;
;               f32x4 ra = *(const LAS f32x4*)(cst + c4), ia = *(const LAS f32x4*)(cst + 64 + c4);
; #pragma unroll
;               for (int ks = 0; ks < 2; ++ks) { ra = MFMA16(wreg[(0 * 4 + n) * 2 + ks], af[ks], ra); ia = MFMA16(wl[((1 * 4 + n) * 2 + ks) * 64 + lane], af[ks], ia); }
;               const f32x4 xv = *(const LAS f32x4*)(xcf + tt * XS + c4);
;               const f32x4 spv = *(const LAS f32x4*)(cst + 128 + c4);
;               f32x4 av, bv;
; #pragma unroll
;               for (int i = 0; i < 4; ++i) { const float r = __builtin_amdgcn_rcpf(1.0f + __builtin_amdgcn_exp2f(ra[i])), ig = __builtin_amdgcn_rcpf(1.0f + __builtin_amdgcn_exp2f(ia[i]));
;                   const float a = __builtin_amdgcn_exp2f(r * spv[i]); const float em = fmaf(-a, a, 1.0f);
;                   av[i] = valid ? a : 1.0f; bv[i] = valid ? __builtin_amdgcn_sqrtf(fmaxf(em, 0.0f)) * ig * xv[i] : 0.0f; }
;               *(LAS f32x4*)(al + tt * 64 + c4) = av; *(LAS f32x4*)(bl + tt * 64 + c4) = bv; } }
.Lgp_nomask_dir0_0:
	ds_write_b128 v224, v[96:99] offset:6784
	ds_write_b128 v224, v[112:115] offset:10880
	ds_read_b128 v[96:99], v135
	ds_read_b128 v[100:103], v136
	ds_read_b128 v[104:107], v122 offset:12288
	ds_read_b128 v[228:231], v122 offset:13312
	v_exp_f32_e32 v232, v232
	v_exp_f32_e32 v233, v233
	v_exp_f32_e32 v234, v234
	v_exp_f32_e32 v235, v235
	v_exp_f32_e32 v236, v236
	v_exp_f32_e32 v237, v237
	v_exp_f32_e32 v238, v238
	v_exp_f32_e32 v239, v239
	v_add_f32_e32 v232, 1.0, v232
	v_add_f32_e32 v233, 1.0, v233
	v_add_f32_e32 v234, 1.0, v234
	v_add_f32_e32 v235, 1.0, v235
	v_add_f32_e32 v236, 1.0, v236
	v_add_f32_e32 v237, 1.0, v237
	v_add_f32_e32 v238, 1.0, v238
	v_add_f32_e32 v239, 1.0, v239
	v_rcp_f32_e32 v232, v232
	v_rcp_f32_e32 v233, v233
	v_rcp_f32_e32 v234, v234
	v_rcp_f32_e32 v235, v235
	v_rcp_f32_e32 v236, v236
	v_rcp_f32_e32 v237, v237
	v_rcp_f32_e32 v238, v238
	v_rcp_f32_e32 v239, v239
	s_waitcnt lgkmcnt(0)
	v_mfma_f32_16x16x32_bf16 v[96:99], v[60:63], v[88:91], v[96:99]
	v_mfma_f32_16x16x32_bf16 v[100:103], v[104:107], v[88:91], v[100:103]
	v_mfma_f32_16x16x32_bf16 v[96:99], v[64:67], v[92:95], v[96:99]
	v_mfma_f32_16x16x32_bf16 v[100:103], v[228:231], v[92:95], v[100:103]
	ds_read_b128 v[104:107], v137
	ds_read_b128 v[228:231], v129 offset:2560
	v_mul_f32_e32 v232, v232, v240
	v_mul_f32_e32 v233, v233, v241
	v_mul_f32_e32 v234, v234, v242
	v_mul_f32_e32 v235, v235, v243
	v_exp_f32_e32 v232, v232
	v_exp_f32_e32 v233, v233
	v_exp_f32_e32 v234, v234
	v_exp_f32_e32 v235, v235
	v_fma_f32 v112, -v232, v232, 1.0
	v_fma_f32 v113, -v233, v233, 1.0
	v_fma_f32 v114, -v234, v234, 1.0
	v_fma_f32 v115, -v235, v235, 1.0
	v_max_f32_e32 v112, 0, v112
	v_max_f32_e32 v113, 0, v113
	v_max_f32_e32 v114, 0, v114
	v_max_f32_e32 v115, 0, v115
	v_sqrt_f32_e32 v112, v112
	v_sqrt_f32_e32 v113, v113
	v_sqrt_f32_e32 v114, v114
	v_sqrt_f32_e32 v115, v115
	v_mul_f32_e32 v236, v236, v112
	v_mul_f32_e32 v237, v237, v113
	v_mul_f32_e32 v238, v238, v114
	v_mul_f32_e32 v239, v239, v115
	v_mul_f32_e32 v112, v108, v236
	v_mul_f32_e32 v113, v109, v237
	v_mul_f32_e32 v114, v110, v238
	v_mul_f32_e32 v115, v111, v239
	s_cmp_eq_u64 s[16:17], exec
	s_cbranch_scc1 .Lgp_nomask_dir0_1
	v_cndmask_b32_e64 v112, 0, v112, s[16:17]
	v_cndmask_b32_e64 v113, 0, v113, s[16:17]
	v_cndmask_b32_e64 v114, 0, v114, s[16:17]
	v_cndmask_b32_e64 v115, 0, v115, s[16:17]
	v_cndmask_b32_e64 v232, 1.0, v232, s[16:17]
	v_cndmask_b32_e64 v233, 1.0, v233, s[16:17]
	v_cndmask_b32_e64 v234, 1.0, v234, s[16:17]
	v_cndmask_b32_e64 v235, 1.0, v235, s[16:17]
.Lgp_nomask_dir0_1:
	ds_write_b128 v225, v[232:235] offset:6784
	ds_write_b128 v225, v[112:115] offset:10880
	ds_read_b128 v[232:235], v138
	ds_read_b128 v[236:239], v139
	ds_read_b128 v[240:243], v122 offset:14336
	ds_read_b128 v[108:111], v122 offset:15360
	v_exp_f32_e32 v96, v96
	v_exp_f32_e32 v97, v97
	v_exp_f32_e32 v98, v98
	v_exp_f32_e32 v99, v99
	v_exp_f32_e32 v100, v100
	v_exp_f32_e32 v101, v101
	v_exp_f32_e32 v102, v102
	v_exp_f32_e32 v103, v103
	v_add_f32_e32 v96, 1.0, v96
	v_add_f32_e32 v97, 1.0, v97
	v_add_f32_e32 v98, 1.0, v98
	v_add_f32_e32 v99, 1.0, v99
	v_add_f32_e32 v100, 1.0, v100
	v_add_f32_e32 v101, 1.0, v101
	v_add_f32_e32 v102, 1.0, v102
	v_add_f32_e32 v103, 1.0, v103
	v_rcp_f32_e32 v96, v96
	v_rcp_f32_e32 v97, v97
	v_rcp_f32_e32 v98, v98
	v_rcp_f32_e32 v99, v99
	v_rcp_f32_e32 v100, v100
	v_rcp_f32_e32 v101, v101
	v_rcp_f32_e32 v102, v102
	v_rcp_f32_e32 v103, v103
	s_waitcnt lgkmcnt(0)
	v_mfma_f32_16x16x32_bf16 v[232:235], v[68:71], v[88:91], v[232:235]
	v_mfma_f32_16x16x32_bf16 v[236:239], v[240:243], v[88:91], v[236:239]
	v_mfma_f32_16x16x32_bf16 v[232:235], v[72:75], v[92:95], v[232:235]
	v_mfma_f32_16x16x32_bf16 v[236:239], v[108:111], v[92:95], v[236:239]
	ds_read_b128 v[240:243], v154
	ds_read_b128 v[108:111], v129 offset:2624
	v_mul_f32_e32 v96, v96, v104
	v_mul_f32_e32 v97, v97, v105
	v_mul_f32_e32 v98, v98, v106
	v_mul_f32_e32 v99, v99, v107
	v_exp_f32_e32 v96, v96
	v_exp_f32_e32 v97, v97
	v_exp_f32_e32 v98, v98
	v_exp_f32_e32 v99, v99
	v_fma_f32 v112, -v96, v96, 1.0
	v_fma_f32 v113, -v97, v97, 1.0
	v_fma_f32 v114, -v98, v98, 1.0
	v_fma_f32 v115, -v99, v99, 1.0
	v_max_f32_e32 v112, 0, v112
	v_max_f32_e32 v113, 0, v113
	v_max_f32_e32 v114, 0, v114
	v_max_f32_e32 v115, 0, v115
	v_sqrt_f32_e32 v112, v112
	v_sqrt_f32_e32 v113, v113
	v_sqrt_f32_e32 v114, v114
	v_sqrt_f32_e32 v115, v115
	v_mul_f32_e32 v100, v100, v112
	v_mul_f32_e32 v101, v101, v113
	v_mul_f32_e32 v102, v102, v114
	v_mul_f32_e32 v103, v103, v115
	v_mul_f32_e32 v112, v228, v100
	v_mul_f32_e32 v113, v229, v101
	v_mul_f32_e32 v114, v230, v102
	v_mul_f32_e32 v115, v231, v103
	s_cmp_eq_u64 s[16:17], exec
	s_cbranch_scc1 .Lgp_nomask_dir0_2
	v_cndmask_b32_e64 v112, 0, v112, s[16:17]
	v_cndmask_b32_e64 v113, 0, v113, s[16:17]
	v_cndmask_b32_e64 v114, 0, v114, s[16:17]
	v_cndmask_b32_e64 v115, 0, v115, s[16:17]
	v_cndmask_b32_e64 v96, 1.0, v96, s[16:17]
	v_cndmask_b32_e64 v97, 1.0, v97, s[16:17]
	v_cndmask_b32_e64 v98, 1.0, v98, s[16:17]
	v_cndmask_b32_e64 v99, 1.0, v99, s[16:17]

; #define LAS __attribute__((address_space(3)))
; __device__ __forceinline__ unsigned cvt_pk(float lo, float hi) { unsigned r; asm("v_cvt_pk_bf16_f32 %0, %1, %2" : "=v"(r) : "v"(lo), "v"(hi)); return r; }
; #define LDS_BARRIER() asm volatile("s_waitcnt lgkmcnt(0)\n\ts_barrier" ::: "memory")
; template <int DIR>
; __device__ __forceinline__ void rnn_scan_unit(const Params& p, LAS unsigned char* lds, int b, int g) {
;     ...
;               *(LAS f32x4*)(al + tt * 64 + c4) = av; *(LAS f32x4*)(bl + tt * 64 + c4) = bv; } }
;         asm volatile("s_waitcnt lgkmcnt(0)" ::: "memory");
;         LAS float* sgA = sg + (ci & 1) * 1024; LAS float* sgB = sgA + 512;
;         float av_[16], bv_[16];
;         { float A = 1.f, B = 0.f;
; #pragma unroll
;           for (int k = 0; k < 16; ++k) { const int tt = DIR == 0 ? k : 15 - k; av_[k] = al[tt * 64 + ch]; bv_[k] = bl[tt * 64 + ch]; B = av_[k] * B + bv_[k]; A *= av_[k]; }
;           sgA[seg * 64 + ch] = A; sgB[seg * 64 + ch] = B; }
;         LDS_BARRIER();
;         float h = hcar, hin = hcar;
; #pragma unroll
;         for (int s = 0; s < 8; ++s) { const int sx = DIR == 0 ? s : 7 - s; hin = (sx == seg) ? h : hin; h = sgA[sx * 64 + ch] * h + sgB[sx * 64 + ch]; }
;         hcar = h;
; #pragma unroll
;         for (int k = 0; k < 16; ++k) { const int tt = DIR == 0 ? k : 15 - k; hin = av_[k] * hin + bv_[k]; bl[tt * 64 + ch] = hin; }
;         asm volatile("s_waitcnt lgkmcnt(0)" ::: "memory");
;         { const int tk = lane >> 2, cq4 = lane & 3;
;           if (t0 + tk < TT) { const LAS float* src = bl + tk * 64 + 16 * cq4;
;               const f32x4 x0 = *(const LAS f32x4*)(src), x1 = *(const LAS f32x4*)(src + 4), x2 = *(const LAS f32x4*)(src + 8), x3 = *(const LAS f32x4*)(src + 12);
;               u32x4 w0, w1; w0.x = cvt_pk(x0[0], x0[1]); w0.y = cvt_pk(x0[2], x0[3]); w0.z = cvt_pk(x1[0], x1[1]); w0.w = cvt_pk(x1[2], x1[3]);
;               w1.x = cvt_pk(x2[0], x2[1]); w1.y = cvt_pk(x2[2], x2[3]); w1.z = cvt_pk(x3[0], x3[1]); w1.w = cvt_pk(x3[2], x3[3]);
;               bf16_t* hp = H + ((size_t)b * TT + t0 + tk) * 512 + 64 * g + 16 * cq4;
;               *(u32x4*)hp = w0; *(u32x4*)(hp + 8) = w1; } }
.Lgp_nomask_dir0_3:
	ds_write_b128 v227, v[232:235] offset:6784
	ds_write_b128 v227, v[112:115] offset:10880
	s_waitcnt lgkmcnt(0)
	ds_read2st64_b32 v[180:181], v212 offset0:26 offset1:34
	ds_read2st64_b32 v[196:197], v212 offset0:42 offset1:50
	ds_read2st64_b32 v[182:183], v213 offset0:27 offset1:35
	ds_read2st64_b32 v[198:199], v213 offset0:43 offset1:51
	ds_read2st64_b32 v[184:185], v214 offset0:28 offset1:36
	ds_read2st64_b32 v[200:201], v214 offset0:44 offset1:52
	ds_read2st64_b32 v[186:187], v215 offset0:29 offset1:37
	ds_read2st64_b32 v[202:203], v215 offset0:45 offset1:53
	ds_read2st64_b32 v[188:189], v216 offset0:30 offset1:38
	ds_read2st64_b32 v[204:205], v216 offset0:46 offset1:54
	ds_read2st64_b32 v[190:191], v217 offset0:31 offset1:39
	ds_read2st64_b32 v[206:207], v217 offset0:47 offset1:55
	ds_read2st64_b32 v[192:193], v218 offset0:32 offset1:40
	ds_read2st64_b32 v[208:209], v218 offset0:48 offset1:56
	ds_read2st64_b32 v[194:195], v219 offset0:33 offset1:41
	ds_read2st64_b32 v[210:211], v219 offset0:49 offset1:57
	s_and_b32 s16, s34, 0x400
	s_lshl_b32 s16, s16, 2
	s_add_i32 s16, s16, 0
	s_add_i32 s16, s16, 0x1d400
	v_lshl_add_u32 v112, v120, 2, s16
	s_waitcnt lgkmcnt(14)
	v_fma_f32 v0, 0, v180, v196
	s_waitcnt lgkmcnt(12)
	v_fma_f32 v0, v0, v182, v198
	v_mul_f32_e32 v2, v180, v182
	s_waitcnt lgkmcnt(10)
	v_fma_f32 v0, v0, v184, v200
	v_mul_f32_e32 v2, v2, v184
	s_waitcnt lgkmcnt(8)
	v_fma_f32 v0, v0, v186, v202
	v_mul_f32_e32 v2, v2, v186
	s_waitcnt lgkmcnt(6)
	v_fma_f32 v0, v0, v188, v204
	v_mul_f32_e32 v2, v2, v188
	s_waitcnt lgkmcnt(4)
	v_fma_f32 v0, v0, v190, v206
	v_mul_f32_e32 v2, v2, v190
	s_waitcnt lgkmcnt(2)
	v_fma_f32 v0, v0, v192, v208
	v_mul_f32_e32 v2, v2, v192
	s_waitcnt lgkmcnt(0)
	v_fma_f32 v0, v0, v194, v210
	v_mul_f32_e32 v2, v2, v194
	v_fma_f32 v0, v0, v181, v197
	v_mul_f32_e32 v2, v2, v181
	v_fma_f32 v0, v0, v183, v199
	v_mul_f32_e32 v2, v2, v183
	v_fma_f32 v0, v0, v185, v201
	v_mul_f32_e32 v2, v2, v185
	v_fma_f32 v0, v0, v187, v203
	v_mul_f32_e32 v2, v2, v187
	v_fma_f32 v0, v0, v189, v205
	v_mul_f32_e32 v2, v2, v189
	v_fma_f32 v0, v0, v191, v207
	v_mul_f32_e32 v2, v2, v191
	v_fma_f32 v0, v0, v193, v209
	v_mul_f32_e32 v2, v2, v193
	v_fma_f32 v0, v0, v195, v211
	v_mul_f32_e32 v2, v2, v195
	ds_write2st64_b32 v112, v2, v0 offset1:8
	s_waitcnt lgkmcnt(0)
	s_barrier
	v_lshl_add_u32 v0, v121, 2, s16
	ds_read2st64_b32 v[112:113], v0 offset1:1
	ds_read2st64_b32 v[174:175], v0 offset0:8 offset1:9
	s_waitcnt lgkmcnt(0)
	v_fma_f32 v2, v3, v112, v174
	v_cndmask_b32_e64 v3, v3, v2, s[0:1]
	v_fmac_f32_e32 v175, v2, v113
	v_cndmask_b32_e64 v174, v3, v175, s[2:3]
	ds_read2st64_b32 v[2:3], v0 offset0:2 offset1:3
	ds_read2st64_b32 v[112:113], v0 offset0:10 offset1:11
	s_waitcnt lgkmcnt(0)
	v_fma_f32 v2, v175, v2, v112
	v_cndmask_b32_e64 v112, v174, v2, s[4:5]
	v_fmac_f32_e32 v113, v2, v3
	ds_read2st64_b32 v[2:3], v0 offset0:4 offset1:5
	ds_read2st64_b32 v[174:175], v0 offset0:12 offset1:13
	v_cndmask_b32_e64 v112, v112, v113, s[8:9]
	s_waitcnt lgkmcnt(0)
	v_fma_f32 v2, v113, v2, v174
	v_cndmask_b32_e64 v112, v112, v2, s[10:11]
	v_fmac_f32_e32 v175, v2, v3
	v_cndmask_b32_e64 v174, v112, v175, s[12:13]
	ds_read2st64_b32 v[112:113], v0 offset0:6 offset1:7
	ds_read2st64_b32 v[2:3], v0 offset0:14 offset1:15
	s_waitcnt lgkmcnt(0)
	v_fma_f32 v0, v175, v112, v2
	v_cndmask_b32_e64 v2, v174, v0, s[14:15]
	v_fma_f32 v196, v180, v2, v196
	v_fma_f32 v198, v182, v196, v198
	v_fma_f32 v200, v184, v198, v200
	v_fma_f32 v202, v186, v200, v202
	v_fma_f32 v204, v188, v202, v204
	v_fma_f32 v206, v190, v204, v206
	v_fma_f32 v208, v192, v206, v208
	v_fma_f32 v210, v194, v208, v210
	v_fma_f32 v197, v181, v210, v197
	ds_write2st64_b32 v212, v196, v197 offset0:42 offset1:50
	v_fma_f32 v199, v183, v197, v199
	ds_write2st64_b32 v213, v198, v199 offset0:43 offset1:51
	v_fma_f32 v201, v185, v199, v201
	ds_write2st64_b32 v214, v200, v201 offset0:44 offset1:52
	v_fma_f32 v203, v187, v201, v203
	ds_write2st64_b32 v215, v202, v203 offset0:45 offset1:53
	v_fma_f32 v205, v189, v203, v205
	ds_write2st64_b32 v216, v204, v205 offset0:46 offset1:54
	v_fma_f32 v207, v191, v205, v207
	ds_write2st64_b32 v217, v206, v207 offset0:47 offset1:55
	v_fma_f32 v209, v193, v207, v209
	ds_write2st64_b32 v218, v208, v209 offset0:48 offset1:56
	v_fma_f32 v211, v195, v209, v211
	ds_write2st64_b32 v219, v210, v211 offset0:49 offset1:57
	s_waitcnt lgkmcnt(0)
	v_add_u32_e32 v2, s19, v158
	v_cmp_gt_i32_e64 s[16:17], s86, v2
	s_waitcnt vmcnt(0)
	s_and_saveexec_b64 s[76:77], s[16:17]
	s_cbranch_execz .LBB0_595
	ds_read_b128 v[88:91], v220 offset:10880
	ds_read_b128 v[92:95], v221 offset:10880
	ds_read_b128 v[96:99], v222 offset:10880
	ds_read_b128 v[100:103], v223 offset:10880
	s_waitcnt lgkmcnt(3)
	v_cvt_pk_bf16_f32 v88, v88, v89
	v_cvt_pk_bf16_f32 v89, v90, v91
	s_waitcnt lgkmcnt(2)
	v_cvt_pk_bf16_f32 v90, v92, v93
	v_cvt_pk_bf16_f32 v91, v94, v95
	s_waitcnt lgkmcnt(1)
	v_cvt_pk_bf16_f32 v92, v96, v97
	v_cvt_pk_bf16_f32 v93, v98, v99
	s_waitcnt lgkmcnt(0)
	v_cvt_pk_bf16_f32 v94, v100, v101
	v_cvt_pk_bf16_f32 v95, v102, v103
	global_store_dwordx4 v[118:119], v[88:91], off
	global_store_dwordx4 v[118:119], v[92:95], off offset:16
	s_branch .LBB0_595
